# epiwide_rs: UQKV ROWSCALE epilogue hand-written: 8 row-scale loads issued together, dwordx4 stores via v_permlane16_swap
# speedup vs baseline: 1.0263x; 1.0044x over previous
; #define PG8_STAGE(bufoff, gbase, voff) do { _Pragma("unroll") for (int _i = 0; _i < 2; ++_i) \
;         __builtin_amdgcn_global_load_lds((const unsigned*)((const char*)(gbase) + (voff)[_i]), (PG8_LAS unsigned*)(lds + (bufoff) + ldsw + _i * 8192), 16, 0, 0); } while (0)
; #define PG8_LDA(dst, b, h) do { _Pragma("unroll") for (int m = 0; m < 4; ++m) _Pragma("unroll") for (int k = 0; k < 2; ++k) dst[m][k] = *(const PG8_LAS bf16x8*)(lds + PG8_SA(b, h) + aoff + m * 2048 + k * 1024); } while (0)
; #define PG8_LDB(dst, b, h) do { _Pragma("unroll") for (int n = 0; n < 2; ++n) _Pragma("unroll") for (int k = 0; k < 2; ++k) dst[n][k] = *(const PG8_LAS bf16x8*)(lds + PG8_SB(b, h) + boff + n * 2048 + k * 1024); } while (0)
; #define PG8_MMA(ai, bj, At, Bt) do { __builtin_amdgcn_s_setprio(1); _Pragma("unroll") for (int m = 0; m < 4; ++m) _Pragma("unroll") for (int n = 0; n < 2; ++n) _Pragma("unroll") for (int k = 0; k < 2; ++k) \
;         acc[ai][bj][m][n] = __builtin_amdgcn_mfma_f32_16x16x32_bf16(Bt[n][k], At[m][k], acc[ai][bj][m][n], 0, 0, 0); __builtin_amdgcn_s_setprio(0); } while (0)
; #define PG8_WAIT_V(n) asm volatile("s_waitcnt vmcnt(" #n ")" ::: "memory")
; #define PG8_WAIT_L(n) asm volatile("s_waitcnt lgkmcnt(" #n ")" ::: "memory")
; template <class Epi>
; __device__ __forceinline__ void gemm_phase(PG8_LAS unsigned char* lds, const Gemm g, const Sched& S, const Epi& E) {
;     ...
;         for (int t = 0; t < nt; t += 2) {
;             const bool last = (t == nt - 2);
;             const char* a1 = cA + (size_t)(t + 1) * kstep;
;             const char* a2 = last ? nA : cA + (size_t)(t + 2) * kstep; const char* b2 = last ? nB : cB + (size_t)(t + 2) * kstep;
;             const char* a3 = a2 + kstep; const char* b3 = b2 + kstep;
;             PG8_LDB(B0, 0, 0); PG8_SCHED; PG8_LDA(At, 0, 0); PG8_STAGE(PG8_SA(1, 1), a1 + hsA, voffA);
;             PG8_WAIT_L(8); PG8_BAR; PG8_WAIT_L(0); PG8_MMA(0, 0, At, B0); PG8_BAR; PG8_SCHED;
;             PG8_LDB(B1, 0, 1); PG8_STAGE(PG8_SB(0, 0), b2, voffB);
;             PG8_BAR; PG8_WAIT_L(0); PG8_MMA(0, 1, At, B1); PG8_BAR;
;             PG8_LDA(At, 0, 1); PG8_STAGE(PG8_SA(0, 0), a2, voffA);
;             PG8_BAR; PG8_WAIT_L(0); PG8_MMA(1, 0, At, B0); PG8_BAR; PG8_SCHED;
;             PG8_STAGE(PG8_SB(0, 1), b2 + hsB, voffB);
;             PG8_WAIT_V(6); PG8_BAR; PG8_MMA(1, 1, At, B1); PG8_BAR;
.LBB0_473:
	s_add_i32 s68, s8, 2
	s_add_u32 s6, s4, 0x100
	s_addc_u32 s7, s5, 0
	s_add_i32 s69, 0, 0x10000
	v_add_u32_e32 v138, s69, v141
	ds_read_b128 v[148:151], v138
	ds_read_b128 v[152:155], v138 offset:1024
	ds_read_b128 v[156:159], v138 offset:2048
	ds_read_b128 v[160:163], v138 offset:3072
	s_cmp_eq_u32 s66, s8
	s_cselect_b32 s8, s42, s6
	s_cselect_b32 s9, s43, s7
	s_cselect_b32 s11, s45, s67
	s_cselect_b32 s10, s44, s37
	v_lshl_add_u64 v[138:139], s[4:5], 0, v[134:135]
	s_add_i32 m0, s57, 0xc000
	ds_read_b128 v[178:181], v146
	ds_read_b128 v[182:185], v146 offset:1024
	ds_read_b128 v[186:189], v146 offset:2048
	ds_read_b128 v[190:193], v146 offset:3072
	ds_read_b128 v[194:197], v146 offset:4096
	ds_read_b128 v[198:201], v146 offset:5120
	ds_read_b128 v[202:205], v146 offset:6144
	ds_read_b128 v[206:209], v146 offset:7168
	global_load_lds_dwordx4 v[138:139], off
	v_lshl_add_u64 v[138:139], s[4:5], 0, v[136:137]
	s_add_i32 m0, s57, 0xe000
	s_nop 0
	global_load_lds_dwordx4 v[138:139], off
	s_waitcnt lgkmcnt(8)
	s_barrier
	s_waitcnt lgkmcnt(0)
	s_setprio 1
	s_waitcnt lgkmcnt(0)
	v_mfma_f32_16x16x32_bf16 v[124:127], v[148:151], v[178:181], v[124:127]
	v_mfma_f32_16x16x32_bf16 v[120:123], v[156:159], v[178:181], v[120:123]
	v_mfma_f32_16x16x32_bf16 v[108:111], v[148:151], v[186:189], v[108:111]
	v_mfma_f32_16x16x32_bf16 v[104:107], v[156:159], v[186:189], v[104:107]
	v_mfma_f32_16x16x32_bf16 v[92:95], v[148:151], v[194:197], v[92:95]
	v_mfma_f32_16x16x32_bf16 v[88:91], v[156:159], v[194:197], v[88:91]
	v_mfma_f32_16x16x32_bf16 v[76:79], v[148:151], v[202:205], v[76:79]
	v_mfma_f32_16x16x32_bf16 v[72:75], v[156:159], v[202:205], v[72:75]
	v_mfma_f32_16x16x32_bf16 v[124:127], v[152:155], v[182:185], v[124:127]
	v_mfma_f32_16x16x32_bf16 v[120:123], v[160:163], v[182:185], v[120:123]
	v_mfma_f32_16x16x32_bf16 v[108:111], v[152:155], v[190:193], v[108:111]
	v_mfma_f32_16x16x32_bf16 v[104:107], v[160:163], v[190:193], v[104:107]
	v_mfma_f32_16x16x32_bf16 v[92:95], v[152:155], v[198:201], v[92:95]
	v_mfma_f32_16x16x32_bf16 v[88:91], v[160:163], v[198:201], v[88:91]
	v_mfma_f32_16x16x32_bf16 v[76:79], v[152:155], v[206:209], v[76:79]
	v_mfma_f32_16x16x32_bf16 v[72:75], v[160:163], v[206:209], v[72:75]
	s_setprio 0
	s_barrier
	s_add_i32 s70, 0, 0x14000
	v_add_u32_e32 v138, s70, v141
	s_add_i32 s4, s69, s54
	ds_read_b128 v[210:213], v138
	ds_read_b128 v[236:239], v138 offset:1024
	ds_read_b128 v[240:243], v138 offset:2048
	ds_read_b128 v[244:247], v138 offset:3072
	v_lshl_add_u64 v[138:139], s[10:11], 0, v[166:167]
	s_mov_b32 m0, s4
	v_lshl_add_u64 v[172:173], s[10:11], 0, v[132:133]
	global_load_lds_dwordx4 v[138:139], off
	s_add_i32 m0, s4, 0x2000
	s_nop 0
	global_load_lds_dwordx4 v[172:173], off
	s_barrier
	s_waitcnt lgkmcnt(0)
	s_setprio 1
	s_waitcnt lgkmcnt(0)
	v_mfma_f32_16x16x32_bf16 v[116:119], v[210:213], v[178:181], v[116:119]
	v_mfma_f32_16x16x32_bf16 v[112:115], v[240:243], v[178:181], v[112:115]
	v_mfma_f32_16x16x32_bf16 v[100:103], v[210:213], v[186:189], v[100:103]
	v_mfma_f32_16x16x32_bf16 v[96:99], v[240:243], v[186:189], v[96:99]
	v_mfma_f32_16x16x32_bf16 v[84:87], v[210:213], v[194:197], v[84:87]
	v_mfma_f32_16x16x32_bf16 v[80:83], v[240:243], v[194:197], v[80:83]
	v_mfma_f32_16x16x32_bf16 v[68:71], v[210:213], v[202:205], v[68:71]
	v_mfma_f32_16x16x32_bf16 v[64:67], v[240:243], v[202:205], v[64:67]
	v_mfma_f32_16x16x32_bf16 v[116:119], v[236:239], v[182:185], v[116:119]
	v_mfma_f32_16x16x32_bf16 v[112:115], v[244:247], v[182:185], v[112:115]
	v_mfma_f32_16x16x32_bf16 v[100:103], v[236:239], v[190:193], v[100:103]
	v_mfma_f32_16x16x32_bf16 v[96:99], v[244:247], v[190:193], v[96:99]
	v_mfma_f32_16x16x32_bf16 v[84:87], v[236:239], v[198:201], v[84:87]
	v_mfma_f32_16x16x32_bf16 v[80:83], v[244:247], v[198:201], v[80:83]
	v_mfma_f32_16x16x32_bf16 v[68:71], v[236:239], v[206:209], v[68:71]
	v_mfma_f32_16x16x32_bf16 v[64:67], v[244:247], v[206:209], v[64:67]
	s_setprio 0
	s_mov_b32 m0, s57
	v_lshl_add_u64 v[174:175], s[8:9], 0, v[128:129]
	s_barrier
	ds_read_b128 v[178:181], v146 offset:16384
	ds_read_b128 v[182:185], v146 offset:17408
	ds_read_b128 v[186:189], v146 offset:18432
	ds_read_b128 v[190:193], v146 offset:19456
	ds_read_b128 v[194:197], v146 offset:20480
	ds_read_b128 v[198:201], v146 offset:21504
	ds_read_b128 v[202:205], v146 offset:22528
	ds_read_b128 v[206:209], v146 offset:23552
	global_load_lds_dwordx4 v[174:175], off
	v_lshl_add_u64 v[214:215], s[8:9], 0, v[130:131]
	s_mov_b32 m0, s58
	s_nop 0
	global_load_lds_dwordx4 v[214:215], off
	s_barrier
	s_waitcnt lgkmcnt(0)
	s_setprio 1
	s_waitcnt lgkmcnt(0)
	v_mfma_f32_16x16x32_bf16 v[60:63], v[148:151], v[178:181], v[60:63]
	v_mfma_f32_16x16x32_bf16 v[56:59], v[156:159], v[178:181], v[56:59]
	v_mfma_f32_16x16x32_bf16 v[44:47], v[148:151], v[186:189], v[44:47]
	v_mfma_f32_16x16x32_bf16 v[40:43], v[156:159], v[186:189], v[40:43]
	v_mfma_f32_16x16x32_bf16 v[28:31], v[148:151], v[194:197], v[28:31]
	v_mfma_f32_16x16x32_bf16 v[24:27], v[156:159], v[194:197], v[24:27]
	v_mfma_f32_16x16x32_bf16 v[12:15], v[148:151], v[202:205], v[12:15]
	v_mfma_f32_16x16x32_bf16 v[8:11], v[156:159], v[202:205], v[8:11]
	v_mfma_f32_16x16x32_bf16 v[60:63], v[152:155], v[182:185], v[60:63]
	v_mfma_f32_16x16x32_bf16 v[56:59], v[160:163], v[182:185], v[56:59]
	v_mfma_f32_16x16x32_bf16 v[44:47], v[152:155], v[190:193], v[44:47]
	v_mfma_f32_16x16x32_bf16 v[40:43], v[160:163], v[190:193], v[40:43]
	v_mfma_f32_16x16x32_bf16 v[28:31], v[152:155], v[198:201], v[28:31]
	v_mfma_f32_16x16x32_bf16 v[24:27], v[160:163], v[198:201], v[24:27]
	v_mfma_f32_16x16x32_bf16 v[12:15], v[152:155], v[206:209], v[12:15]
	v_mfma_f32_16x16x32_bf16 v[8:11], v[160:163], v[206:209], v[8:11]
	s_setprio 0
	s_barrier
; #define PG8_STAGE(bufoff, gbase, voff) do { _Pragma("unroll") for (int _i = 0; _i < 2; ++_i) \
;         __builtin_amdgcn_global_load_lds((const unsigned*)((const char*)(gbase) + (voff)[_i]), (PG8_LAS unsigned*)(lds + (bufoff) + ldsw + _i * 8192), 16, 0, 0); } while (0)
; #define PG8_LDA(dst, b, h) do { _Pragma("unroll") for (int m = 0; m < 4; ++m) _Pragma("unroll") for (int k = 0; k < 2; ++k) dst[m][k] = *(const PG8_LAS bf16x8*)(lds + PG8_SA(b, h) + aoff + m * 2048 + k * 1024); } while (0)
; #define PG8_LDB(dst, b, h) do { _Pragma("unroll") for (int n = 0; n < 2; ++n) _Pragma("unroll") for (int k = 0; k < 2; ++k) dst[n][k] = *(const PG8_LAS bf16x8*)(lds + PG8_SB(b, h) + boff + n * 2048 + k * 1024); } while (0)
; #define PG8_MMA(ai, bj, At, Bt) do { __builtin_amdgcn_s_setprio(1); _Pragma("unroll") for (int m = 0; m < 4; ++m) _Pragma("unroll") for (int n = 0; n < 2; ++n) _Pragma("unroll") for (int k = 0; k < 2; ++k) \
;         acc[ai][bj][m][n] = __builtin_amdgcn_mfma_f32_16x16x32_bf16(Bt[n][k], At[m][k], acc[ai][bj][m][n], 0, 0, 0); __builtin_amdgcn_s_setprio(0); } while (0)
; #define PG8_WAIT_V(n) asm volatile("s_waitcnt vmcnt(" #n ")" ::: "memory")
; #define PG8_WAIT_L(n) asm volatile("s_waitcnt lgkmcnt(" #n ")" ::: "memory")
; #define PG8_BAR __builtin_amdgcn_s_barrier()
; #define PG8_SCHED __builtin_amdgcn_sched_barrier(0)
; template <class Epi>
; __device__ __forceinline__ void gemm_phase(PG8_LAS unsigned char* lds, const Gemm g, const Sched& S, const Epi& E) {
;     ...
;             PG8_WAIT_V(6); PG8_BAR; PG8_MMA(1, 1, At, B1); PG8_BAR;
;             PG8_LDB(B0, 1, 0); PG8_SCHED; PG8_LDA(At, 1, 0); PG8_STAGE(PG8_SA(0, 1), a2 + hsA, voffA);
;             PG8_WAIT_L(8); PG8_BAR; PG8_WAIT_L(0); PG8_MMA(0, 0, At, B0); PG8_BAR; PG8_SCHED;
;             PG8_LDB(B1, 1, 1); PG8_STAGE(PG8_SB(1, 0), b3, voffB);
;             PG8_BAR; PG8_WAIT_L(0); PG8_MMA(0, 1, At, B1); PG8_BAR;
;             PG8_LDA(At, 1, 1); PG8_STAGE(PG8_SA(1, 0), a3, voffA);
;             PG8_BAR; PG8_WAIT_L(0); PG8_MMA(1, 0, At, B0); PG8_BAR; PG8_SCHED;
	s_add_u32 s4, s10, s38
	s_addc_u32 s5, s11, 0
	s_add_i32 s10, s70, s54
	v_lshl_add_u64 v[248:249], s[4:5], 0, v[166:167]
	s_mov_b32 m0, s10
	v_lshl_add_u64 v[250:251], s[4:5], 0, v[132:133]
	global_load_lds_dwordx4 v[248:249], off
	s_add_i32 m0, s10, 0x2000
	s_nop 0
	global_load_lds_dwordx4 v[250:251], off
	s_waitcnt vmcnt(6)
	s_barrier
	s_setprio 1
	v_mfma_f32_16x16x32_bf16 v[52:55], v[210:213], v[178:181], v[52:55]
	v_mfma_f32_16x16x32_bf16 v[48:51], v[240:243], v[178:181], v[48:51]
	v_mfma_f32_16x16x32_bf16 v[36:39], v[210:213], v[186:189], v[36:39]
	v_mfma_f32_16x16x32_bf16 v[32:35], v[240:243], v[186:189], v[32:35]
	v_mfma_f32_16x16x32_bf16 v[20:23], v[210:213], v[194:197], v[20:23]
	v_mfma_f32_16x16x32_bf16 v[16:19], v[240:243], v[194:197], v[16:19]
	v_mfma_f32_16x16x32_bf16 v[4:7], v[210:213], v[202:205], v[4:7]
	v_mfma_f32_16x16x32_bf16 v[0:3], v[240:243], v[202:205], v[0:3]
	v_mfma_f32_16x16x32_bf16 v[52:55], v[236:239], v[182:185], v[52:55]
	v_mfma_f32_16x16x32_bf16 v[48:51], v[244:247], v[182:185], v[48:51]
	v_mfma_f32_16x16x32_bf16 v[36:39], v[236:239], v[190:193], v[36:39]
	v_mfma_f32_16x16x32_bf16 v[32:35], v[244:247], v[190:193], v[32:35]
	v_mfma_f32_16x16x32_bf16 v[20:23], v[236:239], v[198:201], v[20:23]
	v_mfma_f32_16x16x32_bf16 v[16:19], v[244:247], v[198:201], v[16:19]
	v_mfma_f32_16x16x32_bf16 v[4:7], v[236:239], v[206:209], v[4:7]
	v_mfma_f32_16x16x32_bf16 v[0:3], v[244:247], v[206:209], v[0:3]
	s_setprio 0
	s_add_i32 s10, 0, 0x18000
	v_add_u32_e32 v147, s10, v141
	s_barrier
	ds_read_b128 v[148:151], v147
	ds_read_b128 v[152:155], v147 offset:1024
	ds_read_b128 v[156:159], v147 offset:2048
	ds_read_b128 v[160:163], v147 offset:3072
	s_add_u32 s4, s8, 0xb0000
	s_addc_u32 s5, s9, 0
	s_mov_b32 m0, s59
	v_lshl_add_u64 v[210:211], s[4:5], 0, v[128:129]
	ds_read_b128 v[178:181], v146 offset:32768
	ds_read_b128 v[182:185], v146 offset:33792
	ds_read_b128 v[186:189], v146 offset:34816
	ds_read_b128 v[190:193], v146 offset:35840
	ds_read_b128 v[194:197], v146 offset:36864
	ds_read_b128 v[198:201], v146 offset:37888
	ds_read_b128 v[202:205], v146 offset:38912
	ds_read_b128 v[206:209], v146 offset:39936
	global_load_lds_dwordx4 v[210:211], off
	v_lshl_add_u64 v[210:211], s[4:5], 0, v[130:131]
	s_mov_b32 m0, s60
	s_nop 0
	global_load_lds_dwordx4 v[210:211], off
	s_waitcnt lgkmcnt(8)
	s_barrier
	s_waitcnt lgkmcnt(0)
	s_setprio 1
	s_waitcnt lgkmcnt(0)
	v_mfma_f32_16x16x32_bf16 v[124:127], v[148:151], v[178:181], v[124:127]
	v_mfma_f32_16x16x32_bf16 v[120:123], v[156:159], v[178:181], v[120:123]
	v_mfma_f32_16x16x32_bf16 v[108:111], v[148:151], v[186:189], v[108:111]
	v_mfma_f32_16x16x32_bf16 v[104:107], v[156:159], v[186:189], v[104:107]
	v_mfma_f32_16x16x32_bf16 v[92:95], v[148:151], v[194:197], v[92:95]
	v_mfma_f32_16x16x32_bf16 v[88:91], v[156:159], v[194:197], v[88:91]
	v_mfma_f32_16x16x32_bf16 v[76:79], v[148:151], v[202:205], v[76:79]
	v_mfma_f32_16x16x32_bf16 v[72:75], v[156:159], v[202:205], v[72:75]
	v_mfma_f32_16x16x32_bf16 v[124:127], v[152:155], v[182:185], v[124:127]
	v_mfma_f32_16x16x32_bf16 v[120:123], v[160:163], v[182:185], v[120:123]
	v_mfma_f32_16x16x32_bf16 v[108:111], v[152:155], v[190:193], v[108:111]
	v_mfma_f32_16x16x32_bf16 v[104:107], v[160:163], v[190:193], v[104:107]
	v_mfma_f32_16x16x32_bf16 v[92:95], v[152:155], v[198:201], v[92:95]
	v_mfma_f32_16x16x32_bf16 v[88:91], v[160:163], v[198:201], v[88:91]
	v_mfma_f32_16x16x32_bf16 v[76:79], v[152:155], v[206:209], v[76:79]
	v_mfma_f32_16x16x32_bf16 v[72:75], v[160:163], v[206:209], v[72:75]
	s_setprio 0
	s_barrier
	s_add_i32 s4, 0, 0x1c000
	s_add_i32 s5, s10, s54
	v_add_u32_e32 v147, s4, v141
	v_lshl_add_u64 v[138:139], v[138:139], 0, s[76:77]
	s_mov_b32 m0, s5
	ds_read_b128 v[210:213], v147
	ds_read_b128 v[236:239], v147 offset:1024
	ds_read_b128 v[240:243], v147 offset:2048
	ds_read_b128 v[244:247], v147 offset:3072
	global_load_lds_dwordx4 v[138:139], off
	v_lshl_add_u64 v[138:139], v[172:173], 0, s[76:77]
	s_add_i32 m0, s5, 0x2000
	s_nop 0
	global_load_lds_dwordx4 v[138:139], off
	s_barrier
	s_waitcnt lgkmcnt(0)
	s_setprio 1
	s_waitcnt lgkmcnt(0)
	v_mfma_f32_16x16x32_bf16 v[116:119], v[210:213], v[178:181], v[116:119]
	v_mfma_f32_16x16x32_bf16 v[112:115], v[240:243], v[178:181], v[112:115]
	v_mfma_f32_16x16x32_bf16 v[100:103], v[210:213], v[186:189], v[100:103]
	v_mfma_f32_16x16x32_bf16 v[96:99], v[240:243], v[186:189], v[96:99]
	v_mfma_f32_16x16x32_bf16 v[84:87], v[210:213], v[194:197], v[84:87]
	v_mfma_f32_16x16x32_bf16 v[80:83], v[240:243], v[194:197], v[80:83]
	v_mfma_f32_16x16x32_bf16 v[68:71], v[210:213], v[202:205], v[68:71]
	v_mfma_f32_16x16x32_bf16 v[64:67], v[240:243], v[202:205], v[64:67]
	v_mfma_f32_16x16x32_bf16 v[116:119], v[236:239], v[182:185], v[116:119]
	v_mfma_f32_16x16x32_bf16 v[112:115], v[244:247], v[182:185], v[112:115]
	v_mfma_f32_16x16x32_bf16 v[100:103], v[236:239], v[190:193], v[100:103]
	v_mfma_f32_16x16x32_bf16 v[96:99], v[244:247], v[190:193], v[96:99]
	v_mfma_f32_16x16x32_bf16 v[84:87], v[236:239], v[198:201], v[84:87]
	v_mfma_f32_16x16x32_bf16 v[80:83], v[244:247], v[198:201], v[80:83]
	v_mfma_f32_16x16x32_bf16 v[68:71], v[236:239], v[206:209], v[68:71]
	v_mfma_f32_16x16x32_bf16 v[64:67], v[244:247], v[206:209], v[64:67]
	s_setprio 0
	s_mov_b32 m0, s64
	v_lshl_add_u64 v[138:139], v[174:175], 0, s[76:77]
	s_barrier
	ds_read_b128 v[178:181], v146 offset:49152
	ds_read_b128 v[182:185], v146 offset:50176
	ds_read_b128 v[186:189], v146 offset:51200
	ds_read_b128 v[190:193], v146 offset:52224
	ds_read_b128 v[194:197], v146 offset:53248
	ds_read_b128 v[198:201], v146 offset:54272
	ds_read_b128 v[202:205], v146 offset:55296
	ds_read_b128 v[206:209], v146 offset:56320
	global_load_lds_dwordx4 v[138:139], off
	v_lshl_add_u64 v[138:139], v[214:215], 0, s[76:77]
	s_mov_b32 m0, s65
	s_nop 0
	global_load_lds_dwordx4 v[138:139], off
	s_barrier
; __device__ __forceinline__ uint32_t pack2(float a, float b) { uint32_t r; asm("v_cvt_pk_bf16_f32 %0, %1, %2" : "=v"(r) : "v"(a), "v"(b)); return r; }
; #define PG8_STAGE(bufoff, gbase, voff) do { _Pragma("unroll") for (int _i = 0; _i < 2; ++_i) \
;         __builtin_amdgcn_global_load_lds((const unsigned*)((const char*)(gbase) + (voff)[_i]), (PG8_LAS unsigned*)(lds + (bufoff) + ldsw + _i * 8192), 16, 0, 0); } while (0)
; #define PG8_MMA(ai, bj, At, Bt) do { __builtin_amdgcn_s_setprio(1); _Pragma("unroll") for (int m = 0; m < 4; ++m) _Pragma("unroll") for (int n = 0; n < 2; ++n) _Pragma("unroll") for (int k = 0; k < 2; ++k) \
;         acc[ai][bj][m][n] = __builtin_amdgcn_mfma_f32_16x16x32_bf16(Bt[n][k], At[m][k], acc[ai][bj][m][n], 0, 0, 0); __builtin_amdgcn_s_setprio(0); } while (0)
; #define PG8_WAIT_V(n) asm volatile("s_waitcnt vmcnt(" #n ")" ::: "memory")
; #define PG8_WAIT_L(n) asm volatile("s_waitcnt lgkmcnt(" #n ")" ::: "memory")
; #define PG8_BAR __builtin_amdgcn_s_barrier()
; #define PG8_SCHED __builtin_amdgcn_sched_barrier(0)
; template <class Epi>
; __device__ __forceinline__ void gemm_phase(PG8_LAS unsigned char* lds, const Gemm g, const Sched& S, const Epi& E) {
;     ...
;             PG8_BAR; PG8_WAIT_L(0); PG8_MMA(1, 0, At, B0); PG8_BAR; PG8_SCHED;
;             PG8_STAGE(PG8_SB(1, 1), b3 + hsB, voffB);
;             PG8_WAIT_V(6); PG8_BAR; PG8_MMA(1, 1, At, B1); PG8_BAR;
;         }
;         E(acc, cur, wr, wc, fr, fq);
;   __device__ __forceinline__ void operator()(const f32x4 (&acc)[2][2][4][2], const pg8::Unit& u, int wr, int wc, int fr, int fq) const {
;     ...
;         } else {
;           float rsv = (kind == EPI_ROWSCALE) ? rs[(size_t)row * 2] : 1.0f;
; #pragma unroll
;           for (int bj = 0; bj < 2; ++bj)
; #pragma unroll
;             for (int n = 0; n < 2; ++n) {
;               int cc = u.pn * 256 + bj * 128 + wc * 32 + n * 16 + fq * 4;
;               f32x4 a = acc[ai][bj][m][n];
;               uint2 o; o.x = pack2(a[0] * rsv, a[1] * rsv); o.y = pack2(a[2] * rsv, a[3] * rsv);
;               *(uint2*)(outb + (size_t)row * ldo + cc) = o;
;             }
	s_waitcnt lgkmcnt(0)
	s_setprio 1
	s_waitcnt lgkmcnt(0)
	v_mfma_f32_16x16x32_bf16 v[60:63], v[148:151], v[178:181], v[60:63]
	v_mfma_f32_16x16x32_bf16 v[56:59], v[156:159], v[178:181], v[56:59]
	v_mfma_f32_16x16x32_bf16 v[44:47], v[148:151], v[186:189], v[44:47]
	v_mfma_f32_16x16x32_bf16 v[40:43], v[156:159], v[186:189], v[40:43]
	v_mfma_f32_16x16x32_bf16 v[28:31], v[148:151], v[194:197], v[28:31]
	v_mfma_f32_16x16x32_bf16 v[24:27], v[156:159], v[194:197], v[24:27]
	v_mfma_f32_16x16x32_bf16 v[12:15], v[148:151], v[202:205], v[12:15]
	v_mfma_f32_16x16x32_bf16 v[8:11], v[156:159], v[202:205], v[8:11]
	v_mfma_f32_16x16x32_bf16 v[60:63], v[152:155], v[182:185], v[60:63]
	v_mfma_f32_16x16x32_bf16 v[56:59], v[160:163], v[182:185], v[56:59]
	v_mfma_f32_16x16x32_bf16 v[44:47], v[152:155], v[190:193], v[44:47]
	v_mfma_f32_16x16x32_bf16 v[40:43], v[160:163], v[190:193], v[40:43]
	v_mfma_f32_16x16x32_bf16 v[28:31], v[152:155], v[198:201], v[28:31]
	v_mfma_f32_16x16x32_bf16 v[24:27], v[160:163], v[198:201], v[24:27]
	v_mfma_f32_16x16x32_bf16 v[12:15], v[152:155], v[206:209], v[12:15]
	v_mfma_f32_16x16x32_bf16 v[8:11], v[160:163], v[206:209], v[8:11]
	s_setprio 0
	s_barrier
	s_add_i32 s4, s4, s54
	v_lshl_add_u64 v[138:139], v[248:249], 0, s[76:77]
	s_mov_b32 m0, s4
	s_nop 0
	global_load_lds_dwordx4 v[138:139], off
	v_lshl_add_u64 v[138:139], v[250:251], 0, s[76:77]
	s_add_i32 m0, s4, 0x2000
	s_nop 0
	global_load_lds_dwordx4 v[138:139], off
	s_waitcnt vmcnt(6)
	s_barrier
	s_setprio 1
	v_mfma_f32_16x16x32_bf16 v[52:55], v[210:213], v[178:181], v[52:55]
	v_mfma_f32_16x16x32_bf16 v[48:51], v[240:243], v[178:181], v[48:51]
	v_mfma_f32_16x16x32_bf16 v[36:39], v[210:213], v[186:189], v[36:39]
	v_mfma_f32_16x16x32_bf16 v[32:35], v[240:243], v[186:189], v[32:35]
	v_mfma_f32_16x16x32_bf16 v[20:23], v[210:213], v[194:197], v[20:23]
	v_mfma_f32_16x16x32_bf16 v[16:19], v[240:243], v[194:197], v[16:19]
	v_mfma_f32_16x16x32_bf16 v[4:7], v[210:213], v[202:205], v[4:7]
	v_mfma_f32_16x16x32_bf16 v[0:3], v[240:243], v[202:205], v[0:3]
	v_mfma_f32_16x16x32_bf16 v[52:55], v[236:239], v[182:185], v[52:55]
	v_mfma_f32_16x16x32_bf16 v[48:51], v[244:247], v[182:185], v[48:51]
	v_mfma_f32_16x16x32_bf16 v[36:39], v[236:239], v[190:193], v[36:39]
	v_mfma_f32_16x16x32_bf16 v[32:35], v[244:247], v[190:193], v[32:35]
	v_mfma_f32_16x16x32_bf16 v[20:23], v[236:239], v[198:201], v[20:23]
	v_mfma_f32_16x16x32_bf16 v[16:19], v[244:247], v[198:201], v[16:19]
	v_mfma_f32_16x16x32_bf16 v[4:7], v[236:239], v[206:209], v[4:7]
	v_mfma_f32_16x16x32_bf16 v[0:3], v[244:247], v[206:209], v[0:3]
	s_setprio 0
	s_add_u32 s37, s37, 0x100
	s_addc_u32 s67, s67, 0
	s_cmp_ge_u32 s68, s63
	s_mov_b64 s[4:5], s[6:7]
	s_mov_b32 s8, s68
	s_barrier
	s_cbranch_scc0 .LBB0_473
	s_lshl_b32 s4, s29, 8
	v_add_u32_e32 v178, s4, v140
	v_add_u32_e32 v179, s4, v142
	v_add_u32_e32 v180, s4, v143
	v_add_u32_e32 v181, s4, v144
	v_add_u32_e32 v182, 0x80, v178
	v_add_u32_e32 v183, 0x90, v178
	v_add_u32_e32 v184, 0xa0, v178
	v_add_u32_e32 v185, 0xb0, v178
	v_lshlrev_b32_e32 v236, 3, v178
	global_load_dword v186, v236, s[52:53]
	v_lshlrev_b32_e32 v236, 3, v179
	global_load_dword v187, v236, s[52:53]
	v_lshlrev_b32_e32 v236, 3, v180
	global_load_dword v188, v236, s[52:53]
	v_lshlrev_b32_e32 v236, 3, v181
	global_load_dword v189, v236, s[52:53]
	v_lshlrev_b32_e32 v236, 3, v182
	global_load_dword v190, v236, s[52:53]
	v_lshlrev_b32_e32 v236, 3, v183
	global_load_dword v191, v236, s[52:53]
	v_lshlrev_b32_e32 v236, 3, v184
	global_load_dword v192, v236, s[52:53]
	v_lshlrev_b32_e32 v236, 3, v185
	global_load_dword v193, v236, s[52:53]
	v_and_b32_e32 v237, 16, v231
	v_lshrrev_b32_e32 v238, 1, v237
	v_add_u32_e32 v237, v237, v238
	v_lshl_or_b32 v238, s36, 8, v145
	v_lshl_add_u32 v237, v238, 1, v237
	v_mul_lo_u32 v194, v178, s62
	v_lshl_add_u32 v194, v194, 1, v237
	v_mov_b32_e32 v195, 0
	v_lshl_add_u64 v[194:195], s[50:51], 0, v[194:195]
	v_mul_lo_u32 v196, v179, s62
	v_lshl_add_u32 v196, v196, 1, v237
	v_mov_b32_e32 v197, 0
	v_lshl_add_u64 v[196:197], s[50:51], 0, v[196:197]
	v_mul_lo_u32 v198, v180, s62
	v_lshl_add_u32 v198, v198, 1, v237
	v_mov_b32_e32 v199, 0
	v_lshl_add_u64 v[198:199], s[50:51], 0, v[198:199]
	v_mul_lo_u32 v200, v181, s62
	v_lshl_add_u32 v200, v200, 1, v237
	v_mov_b32_e32 v201, 0
	v_lshl_add_u64 v[200:201], s[50:51], 0, v[200:201]
	v_mul_lo_u32 v202, v182, s62
	v_lshl_add_u32 v202, v202, 1, v237
	v_mov_b32_e32 v203, 0
	v_lshl_add_u64 v[202:203], s[50:51], 0, v[202:203]
	v_mul_lo_u32 v204, v183, s62
	v_lshl_add_u32 v204, v204, 1, v237
	v_mov_b32_e32 v205, 0
	v_lshl_add_u64 v[204:205], s[50:51], 0, v[204:205]
	v_mul_lo_u32 v206, v184, s62
	v_lshl_add_u32 v206, v206, 1, v237
	v_mov_b32_e32 v207, 0
	v_lshl_add_u64 v[206:207], s[50:51], 0, v[206:207]
	v_mul_lo_u32 v208, v185, s62
	v_lshl_add_u32 v208, v208, 1, v237
	v_mov_b32_e32 v209, 0
	v_lshl_add_u64 v[208:209], s[50:51], 0, v[208:209]
	s_and_b64 vcc, exec, s[40:41]
	s_mov_b32 s36, s2
	s_mov_b32 s29, s3
	s_mov_b64 s[6:7], s[44:45]
	s_mov_b64 s[4:5], s[42:43]
	s_waitcnt vmcnt(0)
; __device__ __forceinline__ uint32_t pack2(float a, float b) { uint32_t r; asm("v_cvt_pk_bf16_f32 %0, %1, %2" : "=v"(r) : "v"(a), "v"(b)); return r; }
;   __device__ __forceinline__ void operator()(const f32x4 (&acc)[2][2][4][2], const pg8::Unit& u, int wr, int wc, int fr, int fq) const {
;     ...
;         } else {
;           float rsv = (kind == EPI_ROWSCALE) ? rs[(size_t)row * 2] : 1.0f;
; #pragma unroll
;           for (int bj = 0; bj < 2; ++bj)
; #pragma unroll
;             for (int n = 0; n < 2; ++n) {
;               int cc = u.pn * 256 + bj * 128 + wc * 32 + n * 16 + fq * 4;
;               f32x4 a = acc[ai][bj][m][n];
;               uint2 o; o.x = pack2(a[0] * rsv, a[1] * rsv); o.y = pack2(a[2] * rsv, a[3] * rsv);
;               *(uint2*)(outb + (size_t)row * ldo + cc) = o;
;             }
	v_mul_f32_e32 v148, v124, v186
	v_mul_f32_e32 v149, v125, v186
	v_cvt_pk_bf16_f32 v148, v148, v149
	v_mul_f32_e32 v149, v126, v186
	v_mul_f32_e32 v239, v127, v186
	v_cvt_pk_bf16_f32 v149, v149, v239
	v_mul_f32_e32 v150, v120, v186
	v_mul_f32_e32 v151, v121, v186
	v_cvt_pk_bf16_f32 v150, v150, v151
	v_mul_f32_e32 v151, v122, v186
	v_mul_f32_e32 v239, v123, v186
	v_cvt_pk_bf16_f32 v151, v151, v239
	s_nop 1
	v_permlane16_swap_b32_e32 v148, v150
	v_permlane16_swap_b32_e32 v149, v151
	global_store_dwordx4 v[194:195], v[148:151], off
	v_mul_f32_e32 v152, v116, v186
	v_mul_f32_e32 v153, v117, v186
	v_cvt_pk_bf16_f32 v152, v152, v153
	v_mul_f32_e32 v153, v118, v186
	v_mul_f32_e32 v239, v119, v186
	v_cvt_pk_bf16_f32 v153, v153, v239
	v_mul_f32_e32 v154, v112, v186
	v_mul_f32_e32 v155, v113, v186
	v_cvt_pk_bf16_f32 v154, v154, v155
	v_mul_f32_e32 v155, v114, v186
	v_mul_f32_e32 v239, v115, v186
	v_cvt_pk_bf16_f32 v155, v155, v239
	s_nop 1
	v_permlane16_swap_b32_e32 v152, v154
	v_permlane16_swap_b32_e32 v153, v155
	global_store_dwordx4 v[194:195], v[152:155], off offset:256
	v_mul_f32_e32 v156, v108, v187
	v_mul_f32_e32 v157, v109, v187
	v_cvt_pk_bf16_f32 v156, v156, v157
	v_mul_f32_e32 v157, v110, v187
	v_mul_f32_e32 v239, v111, v187
	v_cvt_pk_bf16_f32 v157, v157, v239
	v_mul_f32_e32 v158, v104, v187
	v_mul_f32_e32 v159, v105, v187
	v_cvt_pk_bf16_f32 v158, v158, v159
	v_mul_f32_e32 v159, v106, v187
	v_mul_f32_e32 v239, v107, v187
	v_cvt_pk_bf16_f32 v159, v159, v239
	s_nop 1
	v_permlane16_swap_b32_e32 v156, v158
	v_permlane16_swap_b32_e32 v157, v159
	global_store_dwordx4 v[196:197], v[156:159], off
	v_mul_f32_e32 v160, v100, v187
	v_mul_f32_e32 v161, v101, v187
	v_cvt_pk_bf16_f32 v160, v160, v161
	v_mul_f32_e32 v161, v102, v187
	v_mul_f32_e32 v239, v103, v187
	v_cvt_pk_bf16_f32 v161, v161, v239
	v_mul_f32_e32 v162, v96, v187
	v_mul_f32_e32 v163, v97, v187
	v_cvt_pk_bf16_f32 v162, v162, v163
	v_mul_f32_e32 v163, v98, v187
	v_mul_f32_e32 v239, v99, v187
	v_cvt_pk_bf16_f32 v163, v163, v239
	s_nop 1
	v_permlane16_swap_b32_e32 v160, v162
	v_permlane16_swap_b32_e32 v161, v163
	global_store_dwordx4 v[196:197], v[160:163], off offset:256
	v_mul_f32_e32 v148, v92, v188
	v_mul_f32_e32 v149, v93, v188
	v_cvt_pk_bf16_f32 v148, v148, v149
	v_mul_f32_e32 v149, v94, v188
	v_mul_f32_e32 v239, v95, v188
	v_cvt_pk_bf16_f32 v149, v149, v239
	v_mul_f32_e32 v150, v88, v188
	v_mul_f32_e32 v151, v89, v188
	v_cvt_pk_bf16_f32 v150, v150, v151
	v_mul_f32_e32 v151, v90, v188
	v_mul_f32_e32 v239, v91, v188
	v_cvt_pk_bf16_f32 v151, v151, v239
	s_nop 1
	v_permlane16_swap_b32_e32 v148, v150
	v_permlane16_swap_b32_e32 v149, v151
	global_store_dwordx4 v[198:199], v[148:151], off
	v_mul_f32_e32 v152, v84, v188
	v_mul_f32_e32 v153, v85, v188
	v_cvt_pk_bf16_f32 v152, v152, v153
	v_mul_f32_e32 v153, v86, v188
	v_mul_f32_e32 v239, v87, v188
	v_cvt_pk_bf16_f32 v153, v153, v239
	v_mul_f32_e32 v154, v80, v188
	v_mul_f32_e32 v155, v81, v188
	v_cvt_pk_bf16_f32 v154, v154, v155
	v_mul_f32_e32 v155, v82, v188
	v_mul_f32_e32 v239, v83, v188
	v_cvt_pk_bf16_f32 v155, v155, v239
	s_nop 1
	v_permlane16_swap_b32_e32 v152, v154
	v_permlane16_swap_b32_e32 v153, v155
	global_store_dwordx4 v[198:199], v[152:155], off offset:256
	v_mul_f32_e32 v156, v76, v189
	v_mul_f32_e32 v157, v77, v189
	v_cvt_pk_bf16_f32 v156, v156, v157
	v_mul_f32_e32 v157, v78, v189
	v_mul_f32_e32 v239, v79, v189
	v_cvt_pk_bf16_f32 v157, v157, v239
	v_mul_f32_e32 v158, v72, v189
	v_mul_f32_e32 v159, v73, v189
	v_cvt_pk_bf16_f32 v158, v158, v159
	v_mul_f32_e32 v159, v74, v189
	v_mul_f32_e32 v239, v75, v189
	v_cvt_pk_bf16_f32 v159, v159, v239
	s_nop 1
	v_permlane16_swap_b32_e32 v156, v158
	v_permlane16_swap_b32_e32 v157, v159
	global_store_dwordx4 v[200:201], v[156:159], off
	v_mul_f32_e32 v160, v68, v189
	v_mul_f32_e32 v161, v69, v189
	v_cvt_pk_bf16_f32 v160, v160, v161
	v_mul_f32_e32 v161, v70, v189
	v_mul_f32_e32 v239, v71, v189
	v_cvt_pk_bf16_f32 v161, v161, v239
	v_mul_f32_e32 v162, v64, v189
	v_mul_f32_e32 v163, v65, v189
	v_cvt_pk_bf16_f32 v162, v162, v163
	v_mul_f32_e32 v163, v66, v189
	v_mul_f32_e32 v239, v67, v189
	v_cvt_pk_bf16_f32 v163, v163, v239
	s_nop 1
	v_permlane16_swap_b32_e32 v160, v162
	v_permlane16_swap_b32_e32 v161, v163
	global_store_dwordx4 v[200:201], v[160:163], off offset:256
	v_mul_f32_e32 v148, v60, v190
; __device__ __forceinline__ uint32_t pack2(float a, float b) { uint32_t r; asm("v_cvt_pk_bf16_f32 %0, %1, %2" : "=v"(r) : "v"(a), "v"(b)); return r; }
; template <class Epi>
; __device__ __forceinline__ void gemm_phase(PG8_LAS unsigned char* lds, const Gemm g, const Sched& S, const Epi& E) {
;     ...
;         E(acc, cur, wr, wc, fr, fq);
;         if (!has_next) break;
; #pragma unroll
;         for (int a = 0; a < 2; ++a)
; #pragma unroll
;             for (int b = 0; b < 2; ++b)
; #pragma unroll
;                 for (int m = 0; m < 4; ++m)
; #pragma unroll
;                     for (int n = 0; n < 2; ++n) acc[a][b][m][n] = (f32x4){0.f, 0.f, 0.f, 0.f};
;         cur = nxt; cA = nA; cB = nB; ++ui;
;     }
;   __device__ __forceinline__ void operator()(const f32x4 (&acc)[2][2][4][2], const pg8::Unit& u, int wr, int wc, int fr, int fq) const {
;     ...
;         } else {
;           float rsv = (kind == EPI_ROWSCALE) ? rs[(size_t)row * 2] : 1.0f;
; #pragma unroll
;           for (int bj = 0; bj < 2; ++bj)
; #pragma unroll
;             for (int n = 0; n < 2; ++n) {
;               int cc = u.pn * 256 + bj * 128 + wc * 32 + n * 16 + fq * 4;
;               f32x4 a = acc[ai][bj][m][n];
;               uint2 o; o.x = pack2(a[0] * rsv, a[1] * rsv); o.y = pack2(a[2] * rsv, a[3] * rsv);
;               *(uint2*)(outb + (size_t)row * ldo + cc) = o;
;             }
	v_mul_f32_e32 v149, v61, v190
	v_cvt_pk_bf16_f32 v148, v148, v149
	v_mul_f32_e32 v149, v62, v190
	v_mul_f32_e32 v239, v63, v190
	v_cvt_pk_bf16_f32 v149, v149, v239
	v_mul_f32_e32 v150, v56, v190
	v_mul_f32_e32 v151, v57, v190
	v_cvt_pk_bf16_f32 v150, v150, v151
	v_mul_f32_e32 v151, v58, v190
	v_mul_f32_e32 v239, v59, v190
	v_cvt_pk_bf16_f32 v151, v151, v239
	s_nop 1
	v_permlane16_swap_b32_e32 v148, v150
	v_permlane16_swap_b32_e32 v149, v151
	global_store_dwordx4 v[202:203], v[148:151], off
	v_mul_f32_e32 v152, v52, v190
	v_mul_f32_e32 v153, v53, v190
	v_cvt_pk_bf16_f32 v152, v152, v153
	v_mul_f32_e32 v153, v54, v190
	v_mul_f32_e32 v239, v55, v190
	v_cvt_pk_bf16_f32 v153, v153, v239
	v_mul_f32_e32 v154, v48, v190
	v_mul_f32_e32 v155, v49, v190
	v_cvt_pk_bf16_f32 v154, v154, v155
	v_mul_f32_e32 v155, v50, v190
	v_mul_f32_e32 v239, v51, v190
	v_cvt_pk_bf16_f32 v155, v155, v239
	s_nop 1
	v_permlane16_swap_b32_e32 v152, v154
	v_permlane16_swap_b32_e32 v153, v155
	global_store_dwordx4 v[202:203], v[152:155], off offset:256
	v_mul_f32_e32 v156, v44, v191
	v_mul_f32_e32 v157, v45, v191
	v_cvt_pk_bf16_f32 v156, v156, v157
	v_mul_f32_e32 v157, v46, v191
	v_mul_f32_e32 v239, v47, v191
	v_cvt_pk_bf16_f32 v157, v157, v239
	v_mul_f32_e32 v158, v40, v191
	v_mul_f32_e32 v159, v41, v191
	v_cvt_pk_bf16_f32 v158, v158, v159
	v_mul_f32_e32 v159, v42, v191
	v_mul_f32_e32 v239, v43, v191
	v_cvt_pk_bf16_f32 v159, v159, v239
	s_nop 1
	v_permlane16_swap_b32_e32 v156, v158
	v_permlane16_swap_b32_e32 v157, v159
	global_store_dwordx4 v[204:205], v[156:159], off
	v_mul_f32_e32 v160, v36, v191
	v_mul_f32_e32 v161, v37, v191
	v_cvt_pk_bf16_f32 v160, v160, v161
	v_mul_f32_e32 v161, v38, v191
	v_mul_f32_e32 v239, v39, v191
	v_cvt_pk_bf16_f32 v161, v161, v239
	v_mul_f32_e32 v162, v32, v191
	v_mul_f32_e32 v163, v33, v191
	v_cvt_pk_bf16_f32 v162, v162, v163
	v_mul_f32_e32 v163, v34, v191
	v_mul_f32_e32 v239, v35, v191
	v_cvt_pk_bf16_f32 v163, v163, v239
	s_nop 1
	v_permlane16_swap_b32_e32 v160, v162
	v_permlane16_swap_b32_e32 v161, v163
	global_store_dwordx4 v[204:205], v[160:163], off offset:256
	v_mul_f32_e32 v148, v28, v192
	v_mul_f32_e32 v149, v29, v192
	v_cvt_pk_bf16_f32 v148, v148, v149
	v_mul_f32_e32 v149, v30, v192
	v_mul_f32_e32 v239, v31, v192
	v_cvt_pk_bf16_f32 v149, v149, v239
	v_mul_f32_e32 v150, v24, v192
	v_mul_f32_e32 v151, v25, v192
	v_cvt_pk_bf16_f32 v150, v150, v151
	v_mul_f32_e32 v151, v26, v192
	v_mul_f32_e32 v239, v27, v192
	v_cvt_pk_bf16_f32 v151, v151, v239
	s_nop 1
	v_permlane16_swap_b32_e32 v148, v150
	v_permlane16_swap_b32_e32 v149, v151
	global_store_dwordx4 v[206:207], v[148:151], off
	v_mul_f32_e32 v152, v20, v192
	v_mul_f32_e32 v153, v21, v192
	v_cvt_pk_bf16_f32 v152, v152, v153
	v_mul_f32_e32 v153, v22, v192
	v_mul_f32_e32 v239, v23, v192
	v_cvt_pk_bf16_f32 v153, v153, v239
	v_mul_f32_e32 v154, v16, v192
	v_mul_f32_e32 v155, v17, v192
	v_cvt_pk_bf16_f32 v154, v154, v155
	v_mul_f32_e32 v155, v18, v192
	v_mul_f32_e32 v239, v19, v192
	v_cvt_pk_bf16_f32 v155, v155, v239
	s_nop 1
	v_permlane16_swap_b32_e32 v152, v154
	v_permlane16_swap_b32_e32 v153, v155
	global_store_dwordx4 v[206:207], v[152:155], off offset:256
	v_mul_f32_e32 v156, v12, v193
	v_mul_f32_e32 v157, v13, v193
	v_cvt_pk_bf16_f32 v156, v156, v157
	v_mul_f32_e32 v157, v14, v193
	v_mul_f32_e32 v239, v15, v193
	v_cvt_pk_bf16_f32 v157, v157, v239
	v_mul_f32_e32 v158, v8, v193
	v_mul_f32_e32 v159, v9, v193
	v_cvt_pk_bf16_f32 v158, v158, v159
	v_mul_f32_e32 v159, v10, v193
	v_mul_f32_e32 v239, v11, v193
	v_cvt_pk_bf16_f32 v159, v159, v239
	s_nop 1
	v_permlane16_swap_b32_e32 v156, v158
	v_permlane16_swap_b32_e32 v157, v159
	global_store_dwordx4 v[208:209], v[156:159], off
	v_mul_f32_e32 v160, v4, v193
	v_mul_f32_e32 v161, v5, v193
	v_cvt_pk_bf16_f32 v160, v160, v161
	v_mul_f32_e32 v161, v6, v193
	v_mul_f32_e32 v239, v7, v193
	v_cvt_pk_bf16_f32 v161, v161, v239
	v_mul_f32_e32 v162, v0, v193
	v_mul_f32_e32 v163, v1, v193
	v_cvt_pk_bf16_f32 v162, v162, v163
	v_mul_f32_e32 v163, v2, v193
	v_mul_f32_e32 v239, v3, v193
	v_cvt_pk_bf16_f32 v163, v163, v239
	s_nop 1
	v_permlane16_swap_b32_e32 v160, v162
	v_permlane16_swap_b32_e32 v161, v163
	global_store_dwordx4 v[208:209], v[160:163], off offset:256
	s_cbranch_vccz .LBB0_462
	s_waitcnt vmcnt(0)
	s_cmpk_gt_u32 s17, 0xff
	s_cbranch_scc1 .LBB0_452
	s_barrier
	s_branch .LBB0_452
